# phase 0: fp6 table encode with v_cvt_scalef32_2xpk16_fp6_f32 (same RNE e2m3 codes) instead of the software encoder
# baseline (speedup 1.0000x reference)
.LBB0_38:
	v_ashrrev_i32_e32 v31, 31, v30
	v_lshlrev_b64 v[2:3], 12, v[30:31]
	v_lshl_add_u64 v[10:11], v[26:27], 0, v[2:3]
	global_load_dwordx4 v[2:5], v[10:11], off offset:1024
	global_load_dwordx4 v[22:25], v[10:11], off offset:1536
	global_load_dwordx4 v[6:9], v[10:11], off offset:2048
	global_load_dwordx4 v[44:47], v[10:11], off
	global_load_dwordx4 v[48:51], v[10:11], off offset:512
	global_load_dwordx4 v[18:21], v[10:11], off offset:2560
	global_load_dwordx4 v[14:17], v[10:11], off offset:3072
	s_nop 0
	global_load_dwordx4 v[10:13], v[10:11], off offset:3584
	s_waitcnt vmcnt(0)
	v_max_f32_e64 v52, |v44|, |v45|
	v_max_f32_e64 v53, |v46|, |v47|
	v_max_f32_e64 v54, |v48|, |v49|
	v_max_f32_e64 v55, |v50|, |v51|
	v_max_f32_e64 v56, |v2|, |v3|
	v_max_f32_e64 v57, |v4|, |v5|
	v_max_f32_e64 v58, |v22|, |v23|
	v_max_f32_e64 v59, |v24|, |v25|
	v_max_f32_e64 v60, |v6|, |v7|
	v_max_f32_e64 v61, |v8|, |v9|
	v_max_f32_e64 v62, |v18|, |v19|
	v_max_f32_e64 v63, |v20|, |v21|
	v_max_f32_e64 v64, |v14|, |v15|
	v_max_f32_e64 v65, |v16|, |v17|
	v_max_f32_e64 v66, |v10|, |v11|
	v_max_f32_e64 v67, |v12|, |v13|
	v_max3_f32 v52, v52, v53, v54
	v_max3_f32 v55, v55, v56, v57
	v_max3_f32 v58, v58, v59, v60
	v_max3_f32 v61, v61, v62, v63
	v_max3_f32 v64, v64, v65, v66
	v_max3_f32 v52, v52, v55, v58
	v_max3_f32 v61, v61, v64, v67
	v_max_f32_e32 v117, v52, v61
	ds_bpermute_b32 v119, v38, v117
	s_waitcnt lgkmcnt(0)
	v_max_f32_e32 v117, v117, v119
	ds_bpermute_b32 v119, v39, v117
	s_waitcnt lgkmcnt(0)
	v_max_f32_e32 v117, v117, v119
	ds_bpermute_b32 v119, v40, v117
	s_waitcnt lgkmcnt(0)
	v_max_f32_e32 v117, v117, v119
	ds_bpermute_b32 v119, v41, v117
	s_waitcnt lgkmcnt(0)
	v_max_f32_e32 v117, v117, v119
	ds_bpermute_b32 v119, v42, v117
	s_waitcnt lgkmcnt(0)
	v_max_f32_e32 v117, v117, v119
	v_div_scale_f32 v112, s[4:5], v117, v117, s31
	v_rcp_f32_e32 v113, v112
	v_div_scale_f32 v114, vcc, s31, v117, s31
	v_fma_f32 v115, -v112, v113, 1.0
	v_fmac_f32_e32 v113, v115, v113
	v_mul_f32_e32 v115, v114, v113
	v_fma_f32 v116, -v112, v115, v114
	v_fmac_f32_e32 v115, v116, v113
	v_fma_f32 v114, -v112, v115, v114
	v_div_fmas_f32 v114, v114, v113, v115
	v_div_fixup_f32 v114, v114, v117, s31
	v_cmp_lt_f32_e32 vcc, 0, v117
	v_mad_i64_i32 v[32:33], s[4:5], v30, s30, v[28:29]
	s_nop 0
	v_cndmask_b32_e32 v114, 1.0, v114, vcc
	v_mul_f32_e32 v80, v44, v114
	v_mul_f32_e32 v96, v45, v114
	v_mul_f32_e32 v81, v46, v114
	v_mul_f32_e32 v97, v47, v114
	v_mul_f32_e32 v82, v48, v114
	v_mul_f32_e32 v98, v49, v114
	v_mul_f32_e32 v83, v50, v114
	v_mul_f32_e32 v99, v51, v114
	v_mul_f32_e32 v84, v2, v114
	v_mul_f32_e32 v100, v3, v114
	v_mul_f32_e32 v85, v4, v114
	v_mul_f32_e32 v101, v5, v114
	v_mul_f32_e32 v86, v22, v114
	v_mul_f32_e32 v102, v23, v114
	v_mul_f32_e32 v87, v24, v114
	v_mul_f32_e32 v103, v25, v114
	v_mul_f32_e32 v88, v6, v114
	v_mul_f32_e32 v104, v7, v114
	v_mul_f32_e32 v89, v8, v114
	v_mul_f32_e32 v105, v9, v114
	v_mul_f32_e32 v90, v18, v114
	v_mul_f32_e32 v106, v19, v114
	v_mul_f32_e32 v91, v20, v114
	v_mul_f32_e32 v107, v21, v114
	v_mul_f32_e32 v92, v14, v114
	v_mul_f32_e32 v108, v15, v114
	v_mul_f32_e32 v93, v16, v114
	v_mul_f32_e32 v109, v17, v114
	v_mul_f32_e32 v94, v10, v114
	v_mul_f32_e32 v110, v11, v114
	v_mul_f32_e32 v95, v12, v114
	v_mul_f32_e32 v111, v13, v114
	v_mov_b32_e32 v24, v117
	v_mov_b32_e32 v118, 1.0
	v_cvt_scalef32_2xpk16_fp6_f32 v[2:7], v[80:95], v[96:111], v118
	s_nop 1
	global_store_dwordx4 v[32:33], v[2:5], off
	global_store_dwordx2 v[32:33], v[6:7], off offset:16
	s_and_saveexec_b64 s[4:5], s[0:1]
	s_cbranch_execz .LBB0_37
	v_mul_f32_e32 v4, 0x3e088889, v24
	v_lshl_add_u64 v[2:3], v[30:31], 2, s[52:53]
	v_cndmask_b32_e32 v4, 1.0, v4, vcc
	global_store_dword v[2:3], v4, off
	s_branch .LBB0_37

.LBB0_43:
	v_ashrrev_i32_e32 v31, 31, v30
	v_lshlrev_b64 v[2:3], 12, v[30:31]
	v_lshl_add_u64 v[10:11], v[26:27], 0, v[2:3]
	global_load_dwordx4 v[2:5], v[10:11], off offset:1024
	global_load_dwordx4 v[22:25], v[10:11], off offset:1536
	global_load_dwordx4 v[6:9], v[10:11], off offset:2048
	global_load_dwordx4 v[44:47], v[10:11], off
	global_load_dwordx4 v[48:51], v[10:11], off offset:512
	global_load_dwordx4 v[18:21], v[10:11], off offset:2560
	global_load_dwordx4 v[14:17], v[10:11], off offset:3072
	s_nop 0
	global_load_dwordx4 v[10:13], v[10:11], off offset:3584
	s_waitcnt vmcnt(0)
	v_max_f32_e64 v52, |v44|, |v45|
	v_max_f32_e64 v53, |v46|, |v47|
	v_max_f32_e64 v54, |v48|, |v49|
	v_max_f32_e64 v55, |v50|, |v51|
	v_max_f32_e64 v56, |v2|, |v3|
	v_max_f32_e64 v57, |v4|, |v5|
	v_max_f32_e64 v58, |v22|, |v23|
	v_max_f32_e64 v59, |v24|, |v25|
	v_max_f32_e64 v60, |v6|, |v7|
	v_max_f32_e64 v61, |v8|, |v9|
	v_max_f32_e64 v62, |v18|, |v19|
	v_max_f32_e64 v63, |v20|, |v21|
	v_max_f32_e64 v64, |v14|, |v15|
	v_max_f32_e64 v65, |v16|, |v17|
	v_max_f32_e64 v66, |v10|, |v11|
	v_max_f32_e64 v67, |v12|, |v13|
	v_max3_f32 v52, v52, v53, v54
	v_max3_f32 v55, v55, v56, v57
	v_max3_f32 v58, v58, v59, v60
	v_max3_f32 v61, v61, v62, v63
	v_max3_f32 v64, v64, v65, v66
	v_max3_f32 v52, v52, v55, v58
	v_max3_f32 v61, v61, v64, v67
	v_max_f32_e32 v117, v52, v61
	ds_bpermute_b32 v119, v38, v117
	s_waitcnt lgkmcnt(0)
	v_max_f32_e32 v117, v117, v119
	ds_bpermute_b32 v119, v39, v117
	s_waitcnt lgkmcnt(0)
	v_max_f32_e32 v117, v117, v119
	ds_bpermute_b32 v119, v40, v117
	s_waitcnt lgkmcnt(0)
	v_max_f32_e32 v117, v117, v119
	ds_bpermute_b32 v119, v41, v117
	s_waitcnt lgkmcnt(0)
	v_max_f32_e32 v117, v117, v119
	ds_bpermute_b32 v119, v42, v117
	s_waitcnt lgkmcnt(0)
	v_max_f32_e32 v117, v117, v119
	v_div_scale_f32 v112, s[4:5], v117, v117, s31
	v_rcp_f32_e32 v113, v112
	v_div_scale_f32 v114, vcc, s31, v117, s31
	v_fma_f32 v115, -v112, v113, 1.0
	v_fmac_f32_e32 v113, v115, v113
	v_mul_f32_e32 v115, v114, v113
	v_fma_f32 v116, -v112, v115, v114
	v_fmac_f32_e32 v115, v116, v113
	v_fma_f32 v114, -v112, v115, v114
	v_div_fmas_f32 v114, v114, v113, v115
	v_div_fixup_f32 v114, v114, v117, s31
	v_cmp_lt_f32_e32 vcc, 0, v117
	v_mad_i64_i32 v[32:33], s[4:5], v30, s30, v[28:29]
	s_nop 0
	v_cndmask_b32_e32 v114, 1.0, v114, vcc
	v_mul_f32_e32 v80, v44, v114
	v_mul_f32_e32 v96, v45, v114
	v_mul_f32_e32 v81, v46, v114
	v_mul_f32_e32 v97, v47, v114
	v_mul_f32_e32 v82, v48, v114
	v_mul_f32_e32 v98, v49, v114
	v_mul_f32_e32 v83, v50, v114
	v_mul_f32_e32 v99, v51, v114
	v_mul_f32_e32 v84, v2, v114
	v_mul_f32_e32 v100, v3, v114
	v_mul_f32_e32 v85, v4, v114
	v_mul_f32_e32 v101, v5, v114
	v_mul_f32_e32 v86, v22, v114
	v_mul_f32_e32 v102, v23, v114
	v_mul_f32_e32 v87, v24, v114
	v_mul_f32_e32 v103, v25, v114
	v_mul_f32_e32 v88, v6, v114
	v_mul_f32_e32 v104, v7, v114
	v_mul_f32_e32 v89, v8, v114
	v_mul_f32_e32 v105, v9, v114
	v_mul_f32_e32 v90, v18, v114
	v_mul_f32_e32 v106, v19, v114
	v_mul_f32_e32 v91, v20, v114
	v_mul_f32_e32 v107, v21, v114
	v_mul_f32_e32 v92, v14, v114
	v_mul_f32_e32 v108, v15, v114
	v_mul_f32_e32 v93, v16, v114
	v_mul_f32_e32 v109, v17, v114
	v_mul_f32_e32 v94, v10, v114
	v_mul_f32_e32 v110, v11, v114
	v_mul_f32_e32 v95, v12, v114
	v_mul_f32_e32 v111, v13, v114
	v_mov_b32_e32 v24, v117
	v_mov_b32_e32 v118, 1.0
	v_cvt_scalef32_2xpk16_fp6_f32 v[2:7], v[80:95], v[96:111], v118
	s_nop 1
	global_store_dwordx4 v[32:33], v[2:5], off
	global_store_dwordx2 v[32:33], v[6:7], off offset:16
	s_and_saveexec_b64 s[4:5], s[0:1]
	s_cbranch_execz .LBB0_42
	v_mul_f32_e32 v4, 0x3e088889, v24
	v_lshl_add_u64 v[2:3], v[30:31], 2, s[54:55]
	v_cndmask_b32_e32 v4, 1.0, v4, vcc
	global_store_dword v[2:3], v4, off
	s_branch .LBB0_42

.LBB0_48:
	v_ashrrev_i32_e32 v31, 31, v30
	v_lshlrev_b64 v[2:3], 12, v[30:31]
	v_lshl_add_u64 v[10:11], v[26:27], 0, v[2:3]
	global_load_dwordx4 v[2:5], v[10:11], off offset:1024
	global_load_dwordx4 v[22:25], v[10:11], off offset:1536
	global_load_dwordx4 v[6:9], v[10:11], off offset:2048
	global_load_dwordx4 v[44:47], v[10:11], off
	global_load_dwordx4 v[48:51], v[10:11], off offset:512
	global_load_dwordx4 v[18:21], v[10:11], off offset:2560
	global_load_dwordx4 v[14:17], v[10:11], off offset:3072
	s_nop 0
	global_load_dwordx4 v[10:13], v[10:11], off offset:3584
	s_waitcnt vmcnt(0)
	v_max_f32_e64 v52, |v44|, |v45|
	v_max_f32_e64 v53, |v46|, |v47|
	v_max_f32_e64 v54, |v48|, |v49|
	v_max_f32_e64 v55, |v50|, |v51|
	v_max_f32_e64 v56, |v2|, |v3|
	v_max_f32_e64 v57, |v4|, |v5|
	v_max_f32_e64 v58, |v22|, |v23|
	v_max_f32_e64 v59, |v24|, |v25|
	v_max_f32_e64 v60, |v6|, |v7|
	v_max_f32_e64 v61, |v8|, |v9|
	v_max_f32_e64 v62, |v18|, |v19|
	v_max_f32_e64 v63, |v20|, |v21|
	v_max_f32_e64 v64, |v14|, |v15|
	v_max_f32_e64 v65, |v16|, |v17|
	v_max_f32_e64 v66, |v10|, |v11|
	v_max_f32_e64 v67, |v12|, |v13|
	v_max3_f32 v52, v52, v53, v54
	v_max3_f32 v55, v55, v56, v57
	v_max3_f32 v58, v58, v59, v60
	v_max3_f32 v61, v61, v62, v63
	v_max3_f32 v64, v64, v65, v66
	v_max3_f32 v52, v52, v55, v58
	v_max3_f32 v61, v61, v64, v67
	v_max_f32_e32 v117, v52, v61
	ds_bpermute_b32 v119, v38, v117
	s_waitcnt lgkmcnt(0)
	v_max_f32_e32 v117, v117, v119
	ds_bpermute_b32 v119, v39, v117
	s_waitcnt lgkmcnt(0)
	v_max_f32_e32 v117, v117, v119
	ds_bpermute_b32 v119, v40, v117
	s_waitcnt lgkmcnt(0)
	v_max_f32_e32 v117, v117, v119
	ds_bpermute_b32 v119, v41, v117
	s_waitcnt lgkmcnt(0)
	v_max_f32_e32 v117, v117, v119
	ds_bpermute_b32 v119, v42, v117
	s_waitcnt lgkmcnt(0)
	v_max_f32_e32 v117, v117, v119
	v_div_scale_f32 v112, s[4:5], v117, v117, s31
	v_rcp_f32_e32 v113, v112
	v_div_scale_f32 v114, vcc, s31, v117, s31
	v_fma_f32 v115, -v112, v113, 1.0
	v_fmac_f32_e32 v113, v115, v113
	v_mul_f32_e32 v115, v114, v113
	v_fma_f32 v116, -v112, v115, v114
	v_fmac_f32_e32 v115, v116, v113
	v_fma_f32 v114, -v112, v115, v114
	v_div_fmas_f32 v114, v114, v113, v115
	v_div_fixup_f32 v114, v114, v117, s31
	v_cmp_lt_f32_e32 vcc, 0, v117
	v_mad_i64_i32 v[32:33], s[4:5], v30, s30, v[28:29]
	s_nop 0
	v_cndmask_b32_e32 v114, 1.0, v114, vcc
	v_mul_f32_e32 v80, v44, v114
	v_mul_f32_e32 v96, v45, v114
	v_mul_f32_e32 v81, v46, v114
	v_mul_f32_e32 v97, v47, v114
	v_mul_f32_e32 v82, v48, v114
	v_mul_f32_e32 v98, v49, v114
	v_mul_f32_e32 v83, v50, v114
	v_mul_f32_e32 v99, v51, v114
	v_mul_f32_e32 v84, v2, v114
	v_mul_f32_e32 v100, v3, v114
	v_mul_f32_e32 v85, v4, v114
	v_mul_f32_e32 v101, v5, v114
	v_mul_f32_e32 v86, v22, v114
	v_mul_f32_e32 v102, v23, v114
	v_mul_f32_e32 v87, v24, v114
	v_mul_f32_e32 v103, v25, v114
	v_mul_f32_e32 v88, v6, v114
	v_mul_f32_e32 v104, v7, v114
	v_mul_f32_e32 v89, v8, v114
	v_mul_f32_e32 v105, v9, v114
	v_mul_f32_e32 v90, v18, v114
	v_mul_f32_e32 v106, v19, v114
	v_mul_f32_e32 v91, v20, v114
	v_mul_f32_e32 v107, v21, v114
	v_mul_f32_e32 v92, v14, v114
	v_mul_f32_e32 v108, v15, v114
	v_mul_f32_e32 v93, v16, v114
	v_mul_f32_e32 v109, v17, v114
	v_mul_f32_e32 v94, v10, v114
	v_mul_f32_e32 v110, v11, v114
	v_mul_f32_e32 v95, v12, v114
	v_mul_f32_e32 v111, v13, v114
	v_mov_b32_e32 v24, v117
	v_mov_b32_e32 v118, 1.0
	v_cvt_scalef32_2xpk16_fp6_f32 v[2:7], v[80:95], v[96:111], v118
	s_nop 1
	global_store_dwordx4 v[32:33], v[2:5], off
	global_store_dwordx2 v[32:33], v[6:7], off offset:16
	s_and_saveexec_b64 s[4:5], s[0:1]
	s_cbranch_execz .LBB0_47
	v_mul_f32_e32 v4, 0x3e088889, v24
	v_lshl_add_u64 v[2:3], v[30:31], 2, s[28:29]
	v_cndmask_b32_e32 v4, 1.0, v4, vcc
	global_store_dword v[2:3], v4, off
	s_branch .LBB0_47

.LBB0_53:
	v_ashrrev_i32_e32 v31, 31, v30
	v_lshlrev_b64 v[2:3], 12, v[30:31]
	v_lshl_add_u64 v[10:11], v[26:27], 0, v[2:3]
	global_load_dwordx4 v[2:5], v[10:11], off offset:1024
	global_load_dwordx4 v[22:25], v[10:11], off offset:1536
	global_load_dwordx4 v[6:9], v[10:11], off offset:2048
	global_load_dwordx4 v[44:47], v[10:11], off
	global_load_dwordx4 v[48:51], v[10:11], off offset:512
	global_load_dwordx4 v[18:21], v[10:11], off offset:2560
	global_load_dwordx4 v[14:17], v[10:11], off offset:3072
	s_nop 0
	global_load_dwordx4 v[10:13], v[10:11], off offset:3584
	s_waitcnt vmcnt(0)
	v_max_f32_e64 v52, |v44|, |v45|
	v_max_f32_e64 v53, |v46|, |v47|
	v_max_f32_e64 v54, |v48|, |v49|
	v_max_f32_e64 v55, |v50|, |v51|
	v_max_f32_e64 v56, |v2|, |v3|
	v_max_f32_e64 v57, |v4|, |v5|
	v_max_f32_e64 v58, |v22|, |v23|
	v_max_f32_e64 v59, |v24|, |v25|
	v_max_f32_e64 v60, |v6|, |v7|
	v_max_f32_e64 v61, |v8|, |v9|
	v_max_f32_e64 v62, |v18|, |v19|
	v_max_f32_e64 v63, |v20|, |v21|
	v_max_f32_e64 v64, |v14|, |v15|
	v_max_f32_e64 v65, |v16|, |v17|
	v_max_f32_e64 v66, |v10|, |v11|
	v_max_f32_e64 v67, |v12|, |v13|
	v_max3_f32 v52, v52, v53, v54
	v_max3_f32 v55, v55, v56, v57
	v_max3_f32 v58, v58, v59, v60
	v_max3_f32 v61, v61, v62, v63
	v_max3_f32 v64, v64, v65, v66
	v_max3_f32 v52, v52, v55, v58
	v_max3_f32 v61, v61, v64, v67
	v_max_f32_e32 v117, v52, v61
	ds_bpermute_b32 v119, v38, v117
	s_waitcnt lgkmcnt(0)
	v_max_f32_e32 v117, v117, v119
	ds_bpermute_b32 v119, v39, v117
	s_waitcnt lgkmcnt(0)
	v_max_f32_e32 v117, v117, v119
	ds_bpermute_b32 v119, v40, v117
	s_waitcnt lgkmcnt(0)
	v_max_f32_e32 v117, v117, v119
	ds_bpermute_b32 v119, v41, v117
	s_waitcnt lgkmcnt(0)
	v_max_f32_e32 v117, v117, v119
	ds_bpermute_b32 v119, v42, v117
	s_waitcnt lgkmcnt(0)
	v_max_f32_e32 v117, v117, v119
	v_div_scale_f32 v112, s[4:5], v117, v117, s18
	v_rcp_f32_e32 v113, v112
	v_div_scale_f32 v114, vcc, s18, v117, s18
	v_fma_f32 v115, -v112, v113, 1.0
	v_fmac_f32_e32 v113, v115, v113
	v_mul_f32_e32 v115, v114, v113
	v_fma_f32 v116, -v112, v115, v114
	v_fmac_f32_e32 v115, v116, v113
	v_fma_f32 v114, -v112, v115, v114
	v_div_fmas_f32 v114, v114, v113, v115
	v_div_fixup_f32 v114, v114, v117, s18
	v_cmp_lt_f32_e32 vcc, 0, v117
	v_mad_i64_i32 v[32:33], s[4:5], v30, s17, v[28:29]
	s_nop 0
	v_cndmask_b32_e32 v114, 1.0, v114, vcc
	v_mul_f32_e32 v80, v44, v114
	v_mul_f32_e32 v96, v45, v114
	v_mul_f32_e32 v81, v46, v114
	v_mul_f32_e32 v97, v47, v114
	v_mul_f32_e32 v82, v48, v114
	v_mul_f32_e32 v98, v49, v114
	v_mul_f32_e32 v83, v50, v114
	v_mul_f32_e32 v99, v51, v114
	v_mul_f32_e32 v84, v2, v114
	v_mul_f32_e32 v100, v3, v114
	v_mul_f32_e32 v85, v4, v114
	v_mul_f32_e32 v101, v5, v114
	v_mul_f32_e32 v86, v22, v114
	v_mul_f32_e32 v102, v23, v114
	v_mul_f32_e32 v87, v24, v114
	v_mul_f32_e32 v103, v25, v114
	v_mul_f32_e32 v88, v6, v114
	v_mul_f32_e32 v104, v7, v114
	v_mul_f32_e32 v89, v8, v114
	v_mul_f32_e32 v105, v9, v114
	v_mul_f32_e32 v90, v18, v114
	v_mul_f32_e32 v106, v19, v114
	v_mul_f32_e32 v91, v20, v114
	v_mul_f32_e32 v107, v21, v114
	v_mul_f32_e32 v92, v14, v114
	v_mul_f32_e32 v108, v15, v114
	v_mul_f32_e32 v93, v16, v114
	v_mul_f32_e32 v109, v17, v114
	v_mul_f32_e32 v94, v10, v114
	v_mul_f32_e32 v110, v11, v114
	v_mul_f32_e32 v95, v12, v114
	v_mul_f32_e32 v111, v13, v114
	v_mov_b32_e32 v24, v117
	v_mov_b32_e32 v118, 1.0
	v_cvt_scalef32_2xpk16_fp6_f32 v[2:7], v[80:95], v[96:111], v118
	s_nop 1
	global_store_dwordx4 v[32:33], v[2:5], off
	global_store_dwordx2 v[32:33], v[6:7], off offset:16
	s_and_saveexec_b64 s[4:5], s[0:1]
	s_cbranch_execz .LBB0_52
	v_mul_f32_e32 v4, 0x3e088889, v24
	v_lshl_add_u64 v[2:3], v[30:31], 2, s[30:31]
	v_cndmask_b32_e32 v4, 1.0, v4, vcc
	global_store_dword v[2:3], v4, off
	s_branch .LBB0_52
